# diff loop unrolled by 3 (one copy per LDS stage): fragment read addresses loop-invariant with the stage in the offset field, no per-iteration address arithmetic
# speedup vs baseline: 1.0038x; 1.0038x over previous
; DI int opaque_tid() { int t = threadIdx.x; asm volatile("" : "+v"(t)); return t; }
; template <int DV, bool NA> ...
;   const int tid = opaque_tid(), lane = tid & 63;
;   const int h = lane >> 5, r = lane & 31;
;   bf16x8 q[4];
; #pragma unroll
;   for (int ks = 0; ks < 4; ++ks) q[ks] = *(const bf16x8*)(Qp + ks * 16 + h * 8);
; #pragma unroll
;   for (int mv = 0; mv < DV / 32; ++mv)
; #pragma unroll
;     for (int i = 0; i < 16; ++i) o[mv][i] = 0.f;
;   float m_run = -INFINITY, l_run = 0.f;
;   const int lr = tid >> 3, lc = tid & 7;
;   const int wsw = lr * 128 + ((lc ^ ((lr >> 1) & 7)) << 4);
;   u32x4 rk, rv[DV / 64];
;   auto gload = [&](int ti) {
;     const size_t key0 = (size_t)(tile0 + ti) * 64;
;     rk = *(const u32x4*)(Kb + (key0 + lr) * ldk + lc * 8);
; #pragma unroll
;     for (int i = 0; i < DV / 64; ++i) rv[i] = *(const u32x4*)(Vt + (size_t)(lr + 64 * i) * S + key0 + lc * 8);
;   };
;   auto swrite = [&](int st) {
;     char* ks_ = lds + st * ATT_STAGE;
;     *(u32x4*)(ks_ + wsw) = rk;
; #pragma unroll
;     for (int i = 0; i < DV / 64; ++i) *(u32x4*)(ks_ + 8192 + i * 8192 + wsw) = rv[i];
;   };
;   const int pr = (r & 0x13) | ((r & 4) << 1) | ((r & 8) >> 1);
;   const int ksw = (pr >> 1) & 7;
;   const int vsw = (r >> 1) & 7;
;   const int cs_ = NA ? min(max(qc - 8, 0), 48) : 0;
;   __syncthreads();
;   gload(0);
;   swrite(0);
;   if (ntiles > 1) gload(1);
;   __syncthreads();
; #pragma unroll 2
;   for (int ti = 0; ti < ntiles; ++ti) {
;     if (ti + 1 < ntiles) {
;       swrite((ti + 1) & 1);
;       if (ti + 2 < ntiles) gload(ti + 2);
;     }
;     const char* st = lds + (ti & 1) * ATT_STAGE;
.LBB0_294:
	v_or_b32_e32 v0, s20, v198
	v_mov_b32_e32 v26, v204
	v_lshlrev_b64 v[2:3], 1, v[0:1]
	v_lshl_add_u64 v[4:5], v[162:163], 0, v[2:3]
	v_bfe_u32 v27, v26, 5, 1
	v_lshl_add_u64 v[2:3], v[160:161], 0, v[2:3]
	v_lshlrev_b32_e32 v0, 4, v27
	v_ashrrev_i32_e32 v14, 3, v26
	v_lshlrev_b32_e32 v28, 4, v26
	v_lshl_add_u64 v[4:5], v[4:5], 0, v[0:1]
	v_ashrrev_i32_e32 v15, 31, v14
	v_mad_i64_i32 v[2:3], s[22:23], v14, s96, v[2:3]
	v_and_b32_e32 v0, 0x70, v28
	v_add_u32_e32 v10, 64, v14
	v_lshl_add_u64 v[16:17], v[2:3], 0, v[0:1]
	v_lshlrev_b64 v[2:3], v176, v[14:15]
	v_ashrrev_i32_e32 v11, 31, v10
	v_lshlrev_b64 v[18:19], 1, v[2:3]
	v_lshlrev_b64 v[10:11], v176, v[10:11]
	v_lshl_add_u64 v[2:3], v[164:165], 0, v[18:19]
	v_lshlrev_b64 v[22:23], 1, v[10:11]
	global_load_dwordx4 v[124:127], v[4:5], off
	global_load_dwordx4 v[120:123], v[4:5], off offset:32
	global_load_dwordx4 v[116:119], v[4:5], off offset:64
	global_load_dwordx4 v[112:115], v[4:5], off offset:96
	s_barrier
	v_lshl_add_u64 v[20:21], v[2:3], 0, v[0:1]
	global_load_dwordx4 v[2:5], v[16:17], off offset:1024
	global_load_dwordx4 v[6:9], v[20:21], off
	v_lshl_add_u64 v[10:11], v[164:165], 0, v[22:23]
	v_lshl_add_u64 v[24:25], v[10:11], 0, v[0:1]
	v_add_co_u32_e32 v16, vcc, s97, v16
	global_load_dwordx4 v[10:13], v[24:25], off
	s_nop 0
	v_addc_co_u32_e32 v17, vcc, 0, v17, vcc
	global_load_dwordx4 v[132:135], v[20:21], off offset:128
	global_load_dwordx4 v[128:131], v[16:17], off offset:1024
	global_load_dwordx4 v[136:139], v[24:25], off offset:128
	v_lshlrev_b32_e32 v15, 1, v26
	v_lshrrev_b32_e32 v20, 1, v26
	v_lshrrev_b32_e32 v16, 5, v26
	v_and_b32_e32 v17, 19, v26
	v_bfe_u32 v21, v26, 1, 3
	v_lshlrev_b32_e32 v24, 7, v26
	v_xor_b32_e32 v26, v28, v26
	v_and_b32_e32 v28, 8, v15
	v_and_b32_e32 v20, 4, v20
	v_bitop3_b32 v16, v16, v21, 1 bitop3:0x6c
	v_or3_b32 v17, v28, v17, v20
	v_lshlrev_b32_e32 v25, 7, v14
	v_and_b32_e32 v178, 0xf80, v24
	v_or_b32_e32 v24, 4, v27
	v_or_b32_e32 v29, 2, v27
	v_or_b32_e32 v30, 6, v27
	v_bitop3_b32 v31, v27, v21, 2 bitop3:0x36
	v_bitop3_b32 v32, v27, v21, 4 bitop3:0x36
	v_bitop3_b32 v21, v27, v21, 6 bitop3:0x36
	v_lshlrev_b32_e32 v195, 4, v16
	v_lshrrev_b32_e32 v16, 1, v17
	v_mad_i64_i32 v[14:15], s[22:23], v14, s96, 0
	v_and_or_b32 v203, v26, s66, v25
	v_lshlrev_b32_e32 v179, 4, v21
	v_lshlrev_b32_e32 v228, 7, v17
	v_bitop3_b32 v20, v16, v27, 7 bitop3:0x6c
	v_bitop3_b32 v21, v16, v29, 7 bitop3:0x6c
	v_bitop3_b32 v24, v16, v24, 7 bitop3:0x6c
	v_bitop3_b32 v25, v16, v30, 7 bitop3:0x6c
	v_lshl_add_u64 v[16:17], v[0:1], 0, v[18:19]
	v_or_b32_e32 v14, v14, v0
	v_lshl_add_u64 v[170:171], v[166:167], 0, v[16:17]
	v_lshl_add_u64 v[16:17], v[0:1], 0, v[22:23]
	v_add_u32_e32 v0, s20, v198
	s_waitcnt vmcnt(18)
	v_lshlrev_b32_e32 v183, 4, v31
	v_lshlrev_b32_e32 v181, 4, v32
	v_lshlrev_b32_e32 v229, 4, v20
	v_lshlrev_b32_e32 v202, 4, v21
	v_lshlrev_b32_e32 v201, 4, v24
	v_lshlrev_b32_e32 v200, 4, v25
	v_lshl_add_u64 v[172:173], v[166:167], 0, v[16:17]
	v_mov_b32_e32 v180, 0
	v_mov_b32_e32 v182, 0xff800000
	s_mov_b64 s[20:21], 0
	s_mov_b32 s31, 0
	s_waitcnt vmcnt(5)
	ds_write_b128 v203, v[2:5]
	s_waitcnt vmcnt(4)
	ds_write_b128 v203, v[6:9] offset:8192
	s_waitcnt vmcnt(3)
	ds_write_b128 v203, v[10:13] offset:16384
	v_lshl_add_u64 v[2:3], v[0:1], 1, v[14:15]
	v_mov_b32_e32 v14, v1
	v_mov_b32_e32 v15, v1
	v_lshl_add_u64 v[174:175], v[168:169], 0, v[2:3]
	v_mov_b32_e32 v0, v1
	v_mov_b32_e32 v2, v1
	v_mov_b32_e32 v3, v1
	v_mov_b32_e32 v4, v1
	v_mov_b32_e32 v5, v1
	v_mov_b32_e32 v6, v1
	v_mov_b32_e32 v7, v1
	v_mov_b32_e32 v8, v1
	v_mov_b32_e32 v9, v1
	v_mov_b32_e32 v10, v1
	v_mov_b32_e32 v11, v1
	v_mov_b32_e32 v12, v1
	v_mov_b32_e32 v13, v1
	v_mov_b64_e32 v[30:31], v[14:15]
	v_mov_b64_e32 v[46:47], v[14:15]
	v_mov_b64_e32 v[62:63], v[14:15]
	v_mov_b64_e32 v[78:79], v[14:15]
	v_mov_b64_e32 v[28:29], v[12:13]
	v_mov_b64_e32 v[26:27], v[10:11]
	v_mov_b64_e32 v[24:25], v[8:9]
	v_mov_b64_e32 v[22:23], v[6:7]
	v_mov_b64_e32 v[20:21], v[4:5]
	v_mov_b64_e32 v[18:19], v[2:3]
	v_mov_b64_e32 v[16:17], v[0:1]
	v_mov_b64_e32 v[44:45], v[12:13]
	v_mov_b64_e32 v[42:43], v[10:11]
	v_mov_b64_e32 v[40:41], v[8:9]
	v_mov_b64_e32 v[38:39], v[6:7]
	v_mov_b64_e32 v[36:37], v[4:5]
	v_mov_b64_e32 v[34:35], v[2:3]
	v_mov_b64_e32 v[32:33], v[0:1]
	v_mov_b64_e32 v[60:61], v[12:13]
	v_mov_b64_e32 v[58:59], v[10:11]
	v_mov_b64_e32 v[56:57], v[8:9]
	v_mov_b64_e32 v[54:55], v[6:7]
	v_mov_b64_e32 v[52:53], v[4:5]
	v_mov_b64_e32 v[50:51], v[2:3]
	v_mov_b64_e32 v[48:49], v[0:1]
	v_mov_b64_e32 v[76:77], v[12:13]
	v_mov_b64_e32 v[74:75], v[10:11]
	v_mov_b64_e32 v[72:73], v[8:9]
	v_mov_b64_e32 v[70:71], v[6:7]
	v_mov_b64_e32 v[68:69], v[4:5]
	v_mov_b64_e32 v[66:67], v[2:3]
	v_mov_b64_e32 v[64:65], v[0:1]
	v_mov_b32_e32 v182, 0
	s_mov_b32 s100, 0xff800000
	v_mov_b32_e32 v234, 0
	v_mov_b32_e32 v235, 0
	v_mov_b32_e32 v236, 0
	v_mov_b32_e32 v237, 0
	v_mov_b32_e32 v238, 0
	v_mov_b32_e32 v239, 0
	v_mov_b32_e32 v240, 0
	v_mov_b32_e32 v241, 0
	v_mov_b32_e32 v242, 0
	v_mov_b32_e32 v243, 0
	v_mov_b32_e32 v244, 0
	v_mov_b32_e32 v245, 0
	v_mov_b32_e32 v246, 0
	v_mov_b32_e32 v247, 0
	v_mov_b32_e32 v248, 0
	v_mov_b32_e32 v249, 0
	v_add_u32_e32 v159, 0x6000, v203
	s_waitcnt vmcnt(1)
	ds_write_b128 v159, v[128:131]
	ds_write_b128 v159, v[132:135] offset:8192
	s_waitcnt vmcnt(0)
	ds_write_b128 v159, v[136:139] offset:16384
	v_and_b32_e32 v231, 7, v204
	v_bfe_u32 v232, v204, 4, 3
	v_xor_b32_e32 v232, v232, v231
	v_sub_u32_e32 v232, v232, v231
	v_lshlrev_b32_e32 v232, 4, v232
	v_ashrrev_i32_e32 v233, 31, v232
	v_lshl_add_u64 v[174:175], v[174:175], 0, v[232:233]
	v_lshl_add_u64 v[170:171], v[170:171], 0, v[232:233]
	v_lshl_add_u64 v[172:173], v[172:173], 0, v[232:233]
	v_readfirstlane_b32 s23, v185
	v_add_u32_e32 v128, v228, v229
	v_add_u32_e32 v129, v228, v202
	v_add_u32_e32 v130, v228, v201
	v_add_u32_e32 v131, v228, v200
	v_add_u32_e32 v132, v195, v178
	v_add_u32_e32 v132, 0x2000, v132
	v_add_u32_e32 v133, v183, v178
	v_add_u32_e32 v133, 0x2000, v133
	v_add_u32_e32 v134, v181, v178
	v_add_u32_e32 v134, 0x2000, v134
	v_add_u32_e32 v135, v179, v178
	v_add_u32_e32 v135, 0x2000, v135
	v_readfirstlane_b32 s101, v204
	v_readfirstlane_b32 s20, v177
	s_lshr_b32 s101, s101, 6
	s_lshl_b32 s101, s101, 10
	s_waitcnt lgkmcnt(0)
	s_barrier
	s_branch .LBB0_296
.LBB0_296:
	s_add_i32 vcc_lo, s31, 2
	s_cmp_lt_u32 vcc_lo, s23
	s_cbranch_scc0 .Ldf_nodma0
	s_add_u32 m0, s101, 0xc000
	s_nop 0
	global_load_lds_dwordx4 v[174:175], off
	s_add_u32 m0, s101, 0xe000
	v_lshl_add_u64 v[174:175], v[174:175], 0, s[82:83]
	global_load_lds_dwordx4 v[170:171], off
	s_add_u32 m0, s101, 0x10000
	v_lshl_add_u64 v[170:171], v[170:171], 0, s[4:5]
	global_load_lds_dwordx4 v[172:173], off
	v_lshl_add_u64 v[172:173], v[172:173], 0, s[4:5]
	s_branch .Ldf_dmadone0

; #define MFMA(a, b, c) __builtin_amdgcn_mfma_f32_32x32x16_bf16((a), (b), (c), 0, 0, 0)
; DI float fexp2(float x) { return __builtin_amdgcn_exp2f(x); }
; template <int DV, bool NA> ...
;     ...
;       {
;         bf16x8 ka[4], kb_[4];
; #pragma unroll
;         for (int ks = 0; ks < 4; ++ks) {
;           const int co = ((2 * ks + h) ^ ksw) << 4;
;           ka[ks] = *(const bf16x8*)(st + pr * 128 + co);
;           kb_[ks] = *(const bf16x8*)(st + (32 + pr) * 128 + co);
;         }
;         asm volatile("" ::: "memory");
; #pragma unroll
;         for (int ks = 0; ks < 4; ++ks) {
;           s0 = MFMA(ka[ks], q[ks], s0);
;           s1 = MFMA(kb_[ks], q[ks], s1);
;         }
;       }
;       bf16x8 vf0[2][DV / 32];
; #pragma unroll
;       for (int c2 = 0; c2 < 2; ++c2) {
;         const int co = ((2 * c2 + h) ^ vsw) << 4;
; #pragma unroll
;         for (int mv = 0; mv < DV / 32; ++mv) vf0[c2][mv] = *(const bf16x8*)(st + 8192 + (mv * 32 + r) * 128 + co);
;       }
;     ...
;       float ls = 0.f;
; #pragma unroll
;       for (int e = 0; e < 32; ++e) { t[e] = fexp2(t[e] - m_run); ls += t[e]; }
;       l_run += ls;
;       bf16x8 pf[2][2];
; #pragma unroll
;       for (int kb = 0; kb < 2; ++kb)
; #pragma unroll
;         for (int c2 = 0; c2 < 2; ++c2) {
;           const int e0 = kb * 16 + c2 * 8;
;           u32x4 pw = {pk_bf16(t[e0], t[e0 + 1]), pk_bf16(t[e0 + 2], t[e0 + 3]), pk_bf16(t[e0 + 4], t[e0 + 5]), pk_bf16(t[e0 + 6], t[e0 + 7])};
;           pf[kb][c2] = __builtin_bit_cast(bf16x8, pw);
;         }
;       bf16x8 vf1[2][DV / 32];
; #pragma unroll
;       for (int c2 = 0; c2 < 2; ++c2) {
;         const int co = ((4 + 2 * c2 + h) ^ vsw) << 4;
; #pragma unroll
;         for (int mv = 0; mv < DV / 32; ++mv) vf1[c2][mv] = *(const bf16x8*)(st + 8192 + (mv * 32 + r) * 128 + co);
;       }
;       asm volatile("" ::: "memory");
; #pragma unroll
;       for (int c2 = 0; c2 < 2; ++c2)
; #pragma unroll
;         for (int mv = 0; mv < DV / 32; ++mv) o[mv] = MFMA(vf0[c2][mv], pf[0][c2], o[mv]);
; #pragma unroll
;       for (int c2 = 0; c2 < 2; ++c2)
; #pragma unroll
;         for (int mv = 0; mv < DV / 32; ++mv) o[mv] = MFMA(vf1[c2][mv], pf[1][c2], o[mv]);
;     }
;     __syncthreads();
.Ldf_dmadone0:
	ds_read_b128 v[0:3], v128
	ds_read_b128 v[4:7], v128 offset:4096
	ds_read_b128 v[8:11], v129
	ds_read_b128 v[12:15], v129 offset:4096
	s_waitcnt lgkmcnt(2)
	v_mfma_f32_32x32x16_bf16 v[96:111], v[0:3], v[124:127], v[234:249]
	v_mfma_f32_32x32x16_bf16 v[80:95], v[4:7], v[124:127], v[234:249]
	ds_read_b128 v[0:3], v130
	ds_read_b128 v[4:7], v130 offset:4096
	s_waitcnt lgkmcnt(2)
	v_mfma_f32_32x32x16_bf16 v[96:111], v[8:11], v[120:123], v[96:111]
	v_mfma_f32_32x32x16_bf16 v[80:95], v[12:15], v[120:123], v[80:95]
	ds_read_b128 v[8:11], v131
	ds_read_b128 v[12:15], v131 offset:4096
	ds_read_b128 v[140:143], v132
	ds_read_b128 v[144:147], v132 offset:4096
	ds_read_b128 v[148:151], v132 offset:8192
	ds_read_b128 v[152:155], v132 offset:12288
	s_waitcnt lgkmcnt(6)
	v_mfma_f32_32x32x16_bf16 v[96:111], v[0:3], v[116:119], v[96:111]
	v_mfma_f32_32x32x16_bf16 v[80:95], v[4:7], v[116:119], v[80:95]
	s_waitcnt lgkmcnt(4)
	v_mfma_f32_32x32x16_bf16 v[96:111], v[8:11], v[112:115], v[96:111]
	v_mfma_f32_32x32x16_bf16 v[80:95], v[12:15], v[112:115], v[80:95]
	ds_read_b128 v[0:3], v133
	ds_read_b128 v[4:7], v133 offset:4096
	ds_read_b128 v[8:11], v133 offset:8192
	ds_read_b128 v[12:15], v133 offset:12288
.Ldf_exps0:
	s_nop 6
	v_exp_f32_e32 v96, v96
	v_exp_f32_e32 v97, v97
	v_exp_f32_e32 v98, v98
	v_exp_f32_e32 v99, v99
	v_exp_f32_e32 v100, v100
	v_exp_f32_e32 v101, v101
	v_exp_f32_e32 v102, v102
	v_exp_f32_e32 v103, v103
	v_exp_f32_e32 v104, v104
	v_exp_f32_e32 v105, v105
	v_add_f32_e32 v156, v96, v98
	v_add_f32_e32 v157, v97, v99
	v_exp_f32_e32 v106, v106
	v_exp_f32_e32 v107, v107
	v_add_f32_e32 v156, v156, v100
	v_add_f32_e32 v157, v157, v101
	v_exp_f32_e32 v108, v108
	v_exp_f32_e32 v109, v109
	v_add_f32_e32 v156, v156, v102
	v_add_f32_e32 v157, v157, v103
	v_exp_f32_e32 v110, v110
	v_exp_f32_e32 v111, v111
	v_add_f32_e32 v156, v156, v104
	v_add_f32_e32 v157, v157, v105
	v_exp_f32_e32 v80, v80
	v_exp_f32_e32 v81, v81
	v_add_f32_e32 v156, v156, v106
	v_add_f32_e32 v157, v157, v107
	v_exp_f32_e32 v82, v82
	v_exp_f32_e32 v83, v83
	v_add_f32_e32 v156, v156, v108
	v_add_f32_e32 v157, v157, v109
	v_exp_f32_e32 v84, v84
	v_exp_f32_e32 v85, v85
	v_add_f32_e32 v156, v156, v110
	v_add_f32_e32 v157, v157, v111
	v_exp_f32_e32 v86, v86
	v_exp_f32_e32 v87, v87
	v_add_f32_e32 v156, v156, v80
	v_add_f32_e32 v157, v157, v81
	v_exp_f32_e32 v88, v88
	v_exp_f32_e32 v89, v89
	v_add_f32_e32 v156, v156, v82
	v_add_f32_e32 v157, v157, v83
	v_exp_f32_e32 v90, v90
	v_exp_f32_e32 v91, v91
	v_add_f32_e32 v156, v156, v84
	v_add_f32_e32 v157, v157, v85
	v_exp_f32_e32 v92, v92
	v_exp_f32_e32 v93, v93
	v_add_f32_e32 v156, v156, v86
	v_add_f32_e32 v157, v157, v87
	v_exp_f32_e32 v94, v94
	v_exp_f32_e32 v95, v95
	v_add_f32_e32 v156, v156, v88
	v_add_f32_e32 v157, v157, v89
	v_add_f32_e32 v156, v156, v90
	v_add_f32_e32 v157, v157, v91
	v_add_f32_e32 v156, v156, v92
	v_add_f32_e32 v157, v157, v93
	v_add_f32_e32 v156, v156, v94
	v_add_f32_e32 v157, v157, v95
	v_add_f32_e32 v156, v156, v157
	v_cmp_lt_f32_e32 vcc, s100, v156
	s_cbranch_vccnz .Ldf_fixin0
	v_add_f32_e32 v180, v180, v156
	v_cvt_pk_bf16_f32 v96, v96, v97
	v_cvt_pk_bf16_f32 v97, v98, v99
	v_cvt_pk_bf16_f32 v98, v100, v101
	v_cvt_pk_bf16_f32 v99, v102, v103
	s_waitcnt lgkmcnt(4)
	s_nop 0
	v_mfma_f32_32x32x16_bf16 v[64:79], v[140:143], v[96:99], v[64:79]
	v_cvt_pk_bf16_f32 v104, v104, v105
	v_mfma_f32_32x32x16_bf16 v[48:63], v[144:147], v[96:99], v[48:63]
	v_cvt_pk_bf16_f32 v105, v106, v107
	v_mfma_f32_32x32x16_bf16 v[32:47], v[148:151], v[96:99], v[32:47]
	v_cvt_pk_bf16_f32 v106, v108, v109
	v_mfma_f32_32x32x16_bf16 v[16:31], v[152:155], v[96:99], v[16:31]
	v_cvt_pk_bf16_f32 v107, v110, v111
	ds_read_b128 v[140:143], v134
	ds_read_b128 v[144:147], v134 offset:4096
	ds_read_b128 v[148:151], v134 offset:8192
	ds_read_b128 v[152:155], v134 offset:12288
	s_waitcnt lgkmcnt(4)
	v_mfma_f32_32x32x16_bf16 v[64:79], v[0:3], v[104:107], v[64:79]
	v_cvt_pk_bf16_f32 v80, v80, v81
	v_mfma_f32_32x32x16_bf16 v[48:63], v[4:7], v[104:107], v[48:63]
	v_cvt_pk_bf16_f32 v81, v82, v83
	v_mfma_f32_32x32x16_bf16 v[32:47], v[8:11], v[104:107], v[32:47]
	v_cvt_pk_bf16_f32 v82, v84, v85
	v_mfma_f32_32x32x16_bf16 v[16:31], v[12:15], v[104:107], v[16:31]
	v_cvt_pk_bf16_f32 v83, v86, v87
	ds_read_b128 v[0:3], v135
	ds_read_b128 v[4:7], v135 offset:4096
	ds_read_b128 v[8:11], v135 offset:8192
	ds_read_b128 v[12:15], v135 offset:12288
	s_waitcnt lgkmcnt(4)
	v_mfma_f32_32x32x16_bf16 v[64:79], v[140:143], v[80:83], v[64:79]
	v_cvt_pk_bf16_f32 v88, v88, v89
	v_mfma_f32_32x32x16_bf16 v[48:63], v[144:147], v[80:83], v[48:63]
	v_cvt_pk_bf16_f32 v89, v90, v91
	v_mfma_f32_32x32x16_bf16 v[32:47], v[148:151], v[80:83], v[32:47]
	v_cvt_pk_bf16_f32 v90, v92, v93
	v_mfma_f32_32x32x16_bf16 v[16:31], v[152:155], v[80:83], v[16:31]
	v_cvt_pk_bf16_f32 v91, v94, v95
	s_waitcnt lgkmcnt(0)
	s_nop 0
	v_mfma_f32_32x32x16_bf16 v[64:79], v[0:3], v[88:91], v[64:79]
	v_mfma_f32_32x32x16_bf16 v[48:63], v[4:7], v[88:91], v[48:63]
	v_mfma_f32_32x32x16_bf16 v[32:47], v[8:11], v[88:91], v[32:47]
	v_mfma_f32_32x32x16_bf16 v[16:31], v[12:15], v[88:91], v[16:31]
	s_add_i32 s31, s31, 1
	s_waitcnt vmcnt(3)
	s_waitcnt lgkmcnt(0)
	s_barrier
	s_cmp_lg_u32 s31, s20
	s_cbranch_scc0 .Ldf_exit0
.Ldf_top1:
	s_add_i32 vcc_lo, s31, 2
	s_cmp_lt_u32 vcc_lo, s23
	s_cbranch_scc0 .Ldf_nodma1
	s_add_u32 m0, s101, 0x0
	s_nop 0
	global_load_lds_dwordx4 v[174:175], off
	s_add_u32 m0, s101, 0x2000
	v_lshl_add_u64 v[174:175], v[174:175], 0, s[82:83]
	global_load_lds_dwordx4 v[170:171], off
	s_add_u32 m0, s101, 0x4000
	v_lshl_add_u64 v[170:171], v[170:171], 0, s[4:5]
	global_load_lds_dwordx4 v[172:173], off
	v_lshl_add_u64 v[172:173], v[172:173], 0, s[4:5]
	s_branch .Ldf_dmadone1

; #define MFMA(a, b, c) __builtin_amdgcn_mfma_f32_32x32x16_bf16((a), (b), (c), 0, 0, 0)
; DI float fexp2(float x) { return __builtin_amdgcn_exp2f(x); }
; template <int DV, bool NA> ...
;     ...
;       {
;         bf16x8 ka[4], kb_[4];
; #pragma unroll
;         for (int ks = 0; ks < 4; ++ks) {
;           const int co = ((2 * ks + h) ^ ksw) << 4;
;           ka[ks] = *(const bf16x8*)(st + pr * 128 + co);
;           kb_[ks] = *(const bf16x8*)(st + (32 + pr) * 128 + co);
;         }
;         asm volatile("" ::: "memory");
; #pragma unroll
;         for (int ks = 0; ks < 4; ++ks) {
;           s0 = MFMA(ka[ks], q[ks], s0);
;           s1 = MFMA(kb_[ks], q[ks], s1);
;         }
;       }
;       bf16x8 vf0[2][DV / 32];
; #pragma unroll
;       for (int c2 = 0; c2 < 2; ++c2) {
;         const int co = ((2 * c2 + h) ^ vsw) << 4;
; #pragma unroll
;         for (int mv = 0; mv < DV / 32; ++mv) vf0[c2][mv] = *(const bf16x8*)(st + 8192 + (mv * 32 + r) * 128 + co);
;       }
;     ...
;       float ls = 0.f;
; #pragma unroll
;       for (int e = 0; e < 32; ++e) { t[e] = fexp2(t[e] - m_run); ls += t[e]; }
;       l_run += ls;
;       bf16x8 pf[2][2];
; #pragma unroll
;       for (int kb = 0; kb < 2; ++kb)
; #pragma unroll
;         for (int c2 = 0; c2 < 2; ++c2) {
;           const int e0 = kb * 16 + c2 * 8;
;           u32x4 pw = {pk_bf16(t[e0], t[e0 + 1]), pk_bf16(t[e0 + 2], t[e0 + 3]), pk_bf16(t[e0 + 4], t[e0 + 5]), pk_bf16(t[e0 + 6], t[e0 + 7])};
;           pf[kb][c2] = __builtin_bit_cast(bf16x8, pw);
;         }
;       bf16x8 vf1[2][DV / 32];
; #pragma unroll
;       for (int c2 = 0; c2 < 2; ++c2) {
;         const int co = ((4 + 2 * c2 + h) ^ vsw) << 4;
; #pragma unroll
;         for (int mv = 0; mv < DV / 32; ++mv) vf1[c2][mv] = *(const bf16x8*)(st + 8192 + (mv * 32 + r) * 128 + co);
;       }
;       asm volatile("" ::: "memory");
; #pragma unroll
;       for (int c2 = 0; c2 < 2; ++c2)
; #pragma unroll
;         for (int mv = 0; mv < DV / 32; ++mv) o[mv] = MFMA(vf0[c2][mv], pf[0][c2], o[mv]);
; #pragma unroll
;       for (int c2 = 0; c2 < 2; ++c2)
; #pragma unroll
;         for (int mv = 0; mv < DV / 32; ++mv) o[mv] = MFMA(vf1[c2][mv], pf[1][c2], o[mv]);
;     }
;     __syncthreads();
.Ldf_dmadone1:
	ds_read_b128 v[0:3], v128 offset:24576
	ds_read_b128 v[4:7], v128 offset:28672
	ds_read_b128 v[8:11], v129 offset:24576
	ds_read_b128 v[12:15], v129 offset:28672
	s_waitcnt lgkmcnt(2)
	v_mfma_f32_32x32x16_bf16 v[96:111], v[0:3], v[124:127], v[234:249]
	v_mfma_f32_32x32x16_bf16 v[80:95], v[4:7], v[124:127], v[234:249]
	ds_read_b128 v[0:3], v130 offset:24576
	ds_read_b128 v[4:7], v130 offset:28672
	s_waitcnt lgkmcnt(2)
	v_mfma_f32_32x32x16_bf16 v[96:111], v[8:11], v[120:123], v[96:111]
	v_mfma_f32_32x32x16_bf16 v[80:95], v[12:15], v[120:123], v[80:95]
	ds_read_b128 v[8:11], v131 offset:24576
	ds_read_b128 v[12:15], v131 offset:28672
	ds_read_b128 v[140:143], v132 offset:24576
	ds_read_b128 v[144:147], v132 offset:28672
	ds_read_b128 v[148:151], v132 offset:32768
	ds_read_b128 v[152:155], v132 offset:36864
	s_waitcnt lgkmcnt(6)
	v_mfma_f32_32x32x16_bf16 v[96:111], v[0:3], v[116:119], v[96:111]
	v_mfma_f32_32x32x16_bf16 v[80:95], v[4:7], v[116:119], v[80:95]
	s_waitcnt lgkmcnt(4)
	v_mfma_f32_32x32x16_bf16 v[96:111], v[8:11], v[112:115], v[96:111]
	v_mfma_f32_32x32x16_bf16 v[80:95], v[12:15], v[112:115], v[80:95]
	ds_read_b128 v[0:3], v133 offset:24576
	ds_read_b128 v[4:7], v133 offset:28672
	ds_read_b128 v[8:11], v133 offset:32768
	ds_read_b128 v[12:15], v133 offset:36864
.Ldf_exps1:
	s_nop 6
	v_exp_f32_e32 v96, v96
	v_exp_f32_e32 v97, v97
	v_exp_f32_e32 v98, v98
	v_exp_f32_e32 v99, v99
	v_exp_f32_e32 v100, v100
	v_exp_f32_e32 v101, v101
	v_exp_f32_e32 v102, v102
	v_exp_f32_e32 v103, v103
	v_exp_f32_e32 v104, v104
	v_exp_f32_e32 v105, v105
	v_add_f32_e32 v156, v96, v98
	v_add_f32_e32 v157, v97, v99
	v_exp_f32_e32 v106, v106
	v_exp_f32_e32 v107, v107
	v_add_f32_e32 v156, v156, v100
	v_add_f32_e32 v157, v157, v101
	v_exp_f32_e32 v108, v108
	v_exp_f32_e32 v109, v109
	v_add_f32_e32 v156, v156, v102
	v_add_f32_e32 v157, v157, v103
	v_exp_f32_e32 v110, v110
	v_exp_f32_e32 v111, v111
	v_add_f32_e32 v156, v156, v104
	v_add_f32_e32 v157, v157, v105
	v_exp_f32_e32 v80, v80
	v_exp_f32_e32 v81, v81
	v_add_f32_e32 v156, v156, v106
	v_add_f32_e32 v157, v157, v107
	v_exp_f32_e32 v82, v82
	v_exp_f32_e32 v83, v83
	v_add_f32_e32 v156, v156, v108
	v_add_f32_e32 v157, v157, v109
	v_exp_f32_e32 v84, v84
	v_exp_f32_e32 v85, v85
	v_add_f32_e32 v156, v156, v110
	v_add_f32_e32 v157, v157, v111
	v_exp_f32_e32 v86, v86
	v_exp_f32_e32 v87, v87
	v_add_f32_e32 v156, v156, v80
	v_add_f32_e32 v157, v157, v81
	v_exp_f32_e32 v88, v88
	v_exp_f32_e32 v89, v89
	v_add_f32_e32 v156, v156, v82
	v_add_f32_e32 v157, v157, v83
	v_exp_f32_e32 v90, v90
	v_exp_f32_e32 v91, v91
	v_add_f32_e32 v156, v156, v84
	v_add_f32_e32 v157, v157, v85
	v_exp_f32_e32 v92, v92
	v_exp_f32_e32 v93, v93
	v_add_f32_e32 v156, v156, v86
	v_add_f32_e32 v157, v157, v87
	v_exp_f32_e32 v94, v94
	v_exp_f32_e32 v95, v95
	v_add_f32_e32 v156, v156, v88
	v_add_f32_e32 v157, v157, v89
	v_add_f32_e32 v156, v156, v90
	v_add_f32_e32 v157, v157, v91
	v_add_f32_e32 v156, v156, v92
	v_add_f32_e32 v157, v157, v93
	v_add_f32_e32 v156, v156, v94
	v_add_f32_e32 v157, v157, v95
	v_add_f32_e32 v156, v156, v157
	v_cmp_lt_f32_e32 vcc, s100, v156
	s_cbranch_vccnz .Ldf_fixin1
	v_add_f32_e32 v180, v180, v156
	v_cvt_pk_bf16_f32 v96, v96, v97
	v_cvt_pk_bf16_f32 v97, v98, v99
	v_cvt_pk_bf16_f32 v98, v100, v101
	v_cvt_pk_bf16_f32 v99, v102, v103
	s_waitcnt lgkmcnt(4)
	s_nop 0
	v_mfma_f32_32x32x16_bf16 v[64:79], v[140:143], v[96:99], v[64:79]
	v_cvt_pk_bf16_f32 v104, v104, v105
	v_mfma_f32_32x32x16_bf16 v[48:63], v[144:147], v[96:99], v[48:63]
	v_cvt_pk_bf16_f32 v105, v106, v107
	v_mfma_f32_32x32x16_bf16 v[32:47], v[148:151], v[96:99], v[32:47]
	v_cvt_pk_bf16_f32 v106, v108, v109
	v_mfma_f32_32x32x16_bf16 v[16:31], v[152:155], v[96:99], v[16:31]
	v_cvt_pk_bf16_f32 v107, v110, v111
	ds_read_b128 v[140:143], v134 offset:24576
	ds_read_b128 v[144:147], v134 offset:28672
	ds_read_b128 v[148:151], v134 offset:32768
	ds_read_b128 v[152:155], v134 offset:36864
	s_waitcnt lgkmcnt(4)
	v_mfma_f32_32x32x16_bf16 v[64:79], v[0:3], v[104:107], v[64:79]
	v_cvt_pk_bf16_f32 v80, v80, v81
	v_mfma_f32_32x32x16_bf16 v[48:63], v[4:7], v[104:107], v[48:63]
	v_cvt_pk_bf16_f32 v81, v82, v83
	v_mfma_f32_32x32x16_bf16 v[32:47], v[8:11], v[104:107], v[32:47]
	v_cvt_pk_bf16_f32 v82, v84, v85
	v_mfma_f32_32x32x16_bf16 v[16:31], v[12:15], v[104:107], v[16:31]
	v_cvt_pk_bf16_f32 v83, v86, v87
	ds_read_b128 v[0:3], v135 offset:24576
	ds_read_b128 v[4:7], v135 offset:28672
	ds_read_b128 v[8:11], v135 offset:32768
	ds_read_b128 v[12:15], v135 offset:36864
	s_waitcnt lgkmcnt(4)
	v_mfma_f32_32x32x16_bf16 v[64:79], v[140:143], v[80:83], v[64:79]
	v_cvt_pk_bf16_f32 v88, v88, v89
	v_mfma_f32_32x32x16_bf16 v[48:63], v[144:147], v[80:83], v[48:63]
	v_cvt_pk_bf16_f32 v89, v90, v91
	v_mfma_f32_32x32x16_bf16 v[32:47], v[148:151], v[80:83], v[32:47]
	v_cvt_pk_bf16_f32 v90, v92, v93
	v_mfma_f32_32x32x16_bf16 v[16:31], v[152:155], v[80:83], v[16:31]
	v_cvt_pk_bf16_f32 v91, v94, v95
	s_waitcnt lgkmcnt(0)
	s_nop 0
	v_mfma_f32_32x32x16_bf16 v[64:79], v[0:3], v[88:91], v[64:79]
	v_mfma_f32_32x32x16_bf16 v[48:63], v[4:7], v[88:91], v[48:63]
	v_mfma_f32_32x32x16_bf16 v[32:47], v[8:11], v[88:91], v[32:47]
	v_mfma_f32_32x32x16_bf16 v[16:31], v[12:15], v[88:91], v[16:31]
	s_add_i32 s31, s31, 1
	s_waitcnt vmcnt(3)
	s_waitcnt lgkmcnt(0)
	s_barrier
	s_cmp_lg_u32 s31, s20
	s_cbranch_scc0 .Ldf_exit1
.Ldf_top2:
	s_add_i32 vcc_lo, s31, 2
	s_cmp_lt_u32 vcc_lo, s23
	s_cbranch_scc0 .Ldf_nodma2
	s_add_u32 m0, s101, 0x6000
	s_nop 0
	global_load_lds_dwordx4 v[174:175], off
	s_add_u32 m0, s101, 0x8000
	v_lshl_add_u64 v[174:175], v[174:175], 0, s[82:83]
	global_load_lds_dwordx4 v[170:171], off
	s_add_u32 m0, s101, 0xa000
	v_lshl_add_u64 v[170:171], v[170:171], 0, s[4:5]
	global_load_lds_dwordx4 v[172:173], off
	v_lshl_add_u64 v[172:173], v[172:173], 0, s[4:5]
	s_branch .Ldf_dmadone2

; #define MFMA(a, b, c) __builtin_amdgcn_mfma_f32_32x32x16_bf16((a), (b), (c), 0, 0, 0)
; DI float fexp2(float x) { return __builtin_amdgcn_exp2f(x); }
; template <int DV, bool NA> ...
;     ...
;       {
;         bf16x8 ka[4], kb_[4];
; #pragma unroll
;         for (int ks = 0; ks < 4; ++ks) {
;           const int co = ((2 * ks + h) ^ ksw) << 4;
;           ka[ks] = *(const bf16x8*)(st + pr * 128 + co);
;           kb_[ks] = *(const bf16x8*)(st + (32 + pr) * 128 + co);
;         }
;         asm volatile("" ::: "memory");
; #pragma unroll
;         for (int ks = 0; ks < 4; ++ks) {
;           s0 = MFMA(ka[ks], q[ks], s0);
;           s1 = MFMA(kb_[ks], q[ks], s1);
;         }
;       }
;       bf16x8 vf0[2][DV / 32];
; #pragma unroll
;       for (int c2 = 0; c2 < 2; ++c2) {
;         const int co = ((2 * c2 + h) ^ vsw) << 4;
; #pragma unroll
;         for (int mv = 0; mv < DV / 32; ++mv) vf0[c2][mv] = *(const bf16x8*)(st + 8192 + (mv * 32 + r) * 128 + co);
;       }
;     ...
;       float ls = 0.f;
; #pragma unroll
;       for (int e = 0; e < 32; ++e) { t[e] = fexp2(t[e] - m_run); ls += t[e]; }
;       l_run += ls;
;       bf16x8 pf[2][2];
; #pragma unroll
;       for (int kb = 0; kb < 2; ++kb)
; #pragma unroll
;         for (int c2 = 0; c2 < 2; ++c2) {
;           const int e0 = kb * 16 + c2 * 8;
;           u32x4 pw = {pk_bf16(t[e0], t[e0 + 1]), pk_bf16(t[e0 + 2], t[e0 + 3]), pk_bf16(t[e0 + 4], t[e0 + 5]), pk_bf16(t[e0 + 6], t[e0 + 7])};
;           pf[kb][c2] = __builtin_bit_cast(bf16x8, pw);
;         }
;       bf16x8 vf1[2][DV / 32];
; #pragma unroll
;       for (int c2 = 0; c2 < 2; ++c2) {
;         const int co = ((4 + 2 * c2 + h) ^ vsw) << 4;
; #pragma unroll
;         for (int mv = 0; mv < DV / 32; ++mv) vf1[c2][mv] = *(const bf16x8*)(st + 8192 + (mv * 32 + r) * 128 + co);
;       }
;       asm volatile("" ::: "memory");
; #pragma unroll
;       for (int c2 = 0; c2 < 2; ++c2)
; #pragma unroll
;         for (int mv = 0; mv < DV / 32; ++mv) o[mv] = MFMA(vf0[c2][mv], pf[0][c2], o[mv]);
; #pragma unroll
;       for (int c2 = 0; c2 < 2; ++c2)
; #pragma unroll
;         for (int mv = 0; mv < DV / 32; ++mv) o[mv] = MFMA(vf1[c2][mv], pf[1][c2], o[mv]);
;     }
;     __syncthreads();
.Ldf_dmadone2:
	ds_read_b128 v[0:3], v128 offset:49152
	ds_read_b128 v[4:7], v128 offset:53248
	ds_read_b128 v[8:11], v129 offset:49152
	ds_read_b128 v[12:15], v129 offset:53248
	s_waitcnt lgkmcnt(2)
	v_mfma_f32_32x32x16_bf16 v[96:111], v[0:3], v[124:127], v[234:249]
	v_mfma_f32_32x32x16_bf16 v[80:95], v[4:7], v[124:127], v[234:249]
	ds_read_b128 v[0:3], v130 offset:49152
	ds_read_b128 v[4:7], v130 offset:53248
	s_waitcnt lgkmcnt(2)
	v_mfma_f32_32x32x16_bf16 v[96:111], v[8:11], v[120:123], v[96:111]
	v_mfma_f32_32x32x16_bf16 v[80:95], v[12:15], v[120:123], v[80:95]
	ds_read_b128 v[8:11], v131 offset:49152
	ds_read_b128 v[12:15], v131 offset:53248
	ds_read_b128 v[140:143], v132 offset:49152
	ds_read_b128 v[144:147], v132 offset:53248
	ds_read_b128 v[148:151], v132 offset:57344
	ds_read_b128 v[152:155], v132 offset:61440
	s_waitcnt lgkmcnt(6)
	v_mfma_f32_32x32x16_bf16 v[96:111], v[0:3], v[116:119], v[96:111]
	v_mfma_f32_32x32x16_bf16 v[80:95], v[4:7], v[116:119], v[80:95]
	s_waitcnt lgkmcnt(4)
	v_mfma_f32_32x32x16_bf16 v[96:111], v[8:11], v[112:115], v[96:111]
	v_mfma_f32_32x32x16_bf16 v[80:95], v[12:15], v[112:115], v[80:95]
	ds_read_b128 v[0:3], v133 offset:49152
	ds_read_b128 v[4:7], v133 offset:53248
	ds_read_b128 v[8:11], v133 offset:57344
	ds_read_b128 v[12:15], v133 offset:61440
.Ldf_exps2:
	s_nop 6
	v_exp_f32_e32 v96, v96
	v_exp_f32_e32 v97, v97
	v_exp_f32_e32 v98, v98
	v_exp_f32_e32 v99, v99
	v_exp_f32_e32 v100, v100
	v_exp_f32_e32 v101, v101
	v_exp_f32_e32 v102, v102
	v_exp_f32_e32 v103, v103
	v_exp_f32_e32 v104, v104
	v_exp_f32_e32 v105, v105
	v_add_f32_e32 v156, v96, v98
	v_add_f32_e32 v157, v97, v99
	v_exp_f32_e32 v106, v106
	v_exp_f32_e32 v107, v107
	v_add_f32_e32 v156, v156, v100
	v_add_f32_e32 v157, v157, v101
	v_exp_f32_e32 v108, v108
	v_exp_f32_e32 v109, v109
	v_add_f32_e32 v156, v156, v102
	v_add_f32_e32 v157, v157, v103
	v_exp_f32_e32 v110, v110
	v_exp_f32_e32 v111, v111
	v_add_f32_e32 v156, v156, v104
	v_add_f32_e32 v157, v157, v105
	v_exp_f32_e32 v80, v80
	v_exp_f32_e32 v81, v81
	v_add_f32_e32 v156, v156, v106
	v_add_f32_e32 v157, v157, v107
	v_exp_f32_e32 v82, v82
	v_exp_f32_e32 v83, v83
	v_add_f32_e32 v156, v156, v108
	v_add_f32_e32 v157, v157, v109
	v_exp_f32_e32 v84, v84
	v_exp_f32_e32 v85, v85
	v_add_f32_e32 v156, v156, v110
	v_add_f32_e32 v157, v157, v111
	v_exp_f32_e32 v86, v86
	v_exp_f32_e32 v87, v87
	v_add_f32_e32 v156, v156, v80
	v_add_f32_e32 v157, v157, v81
	v_exp_f32_e32 v88, v88
	v_exp_f32_e32 v89, v89
	v_add_f32_e32 v156, v156, v82
	v_add_f32_e32 v157, v157, v83
	v_exp_f32_e32 v90, v90
	v_exp_f32_e32 v91, v91
	v_add_f32_e32 v156, v156, v84
	v_add_f32_e32 v157, v157, v85
	v_exp_f32_e32 v92, v92
	v_exp_f32_e32 v93, v93
	v_add_f32_e32 v156, v156, v86
	v_add_f32_e32 v157, v157, v87
	v_exp_f32_e32 v94, v94
	v_exp_f32_e32 v95, v95
	v_add_f32_e32 v156, v156, v88
	v_add_f32_e32 v157, v157, v89
	v_add_f32_e32 v156, v156, v90
	v_add_f32_e32 v157, v157, v91
	v_add_f32_e32 v156, v156, v92
	v_add_f32_e32 v157, v157, v93
	v_add_f32_e32 v156, v156, v94
	v_add_f32_e32 v157, v157, v95
	v_add_f32_e32 v156, v156, v157
	v_cmp_lt_f32_e32 vcc, s100, v156
	s_cbranch_vccnz .Ldf_fixin2
	v_add_f32_e32 v180, v180, v156
	v_cvt_pk_bf16_f32 v96, v96, v97
	v_cvt_pk_bf16_f32 v97, v98, v99
	v_cvt_pk_bf16_f32 v98, v100, v101
	v_cvt_pk_bf16_f32 v99, v102, v103
	s_waitcnt lgkmcnt(4)
	s_nop 0
	v_mfma_f32_32x32x16_bf16 v[64:79], v[140:143], v[96:99], v[64:79]
	v_cvt_pk_bf16_f32 v104, v104, v105
	v_mfma_f32_32x32x16_bf16 v[48:63], v[144:147], v[96:99], v[48:63]
	v_cvt_pk_bf16_f32 v105, v106, v107
	v_mfma_f32_32x32x16_bf16 v[32:47], v[148:151], v[96:99], v[32:47]
	v_cvt_pk_bf16_f32 v106, v108, v109
	v_mfma_f32_32x32x16_bf16 v[16:31], v[152:155], v[96:99], v[16:31]
	v_cvt_pk_bf16_f32 v107, v110, v111
	ds_read_b128 v[140:143], v134 offset:49152
	ds_read_b128 v[144:147], v134 offset:53248
	ds_read_b128 v[148:151], v134 offset:57344
	ds_read_b128 v[152:155], v134 offset:61440
	s_waitcnt lgkmcnt(4)
	v_mfma_f32_32x32x16_bf16 v[64:79], v[0:3], v[104:107], v[64:79]
	v_cvt_pk_bf16_f32 v80, v80, v81
	v_mfma_f32_32x32x16_bf16 v[48:63], v[4:7], v[104:107], v[48:63]
	v_cvt_pk_bf16_f32 v81, v82, v83
	v_mfma_f32_32x32x16_bf16 v[32:47], v[8:11], v[104:107], v[32:47]
	v_cvt_pk_bf16_f32 v82, v84, v85
	v_mfma_f32_32x32x16_bf16 v[16:31], v[12:15], v[104:107], v[16:31]
	v_cvt_pk_bf16_f32 v83, v86, v87
	ds_read_b128 v[0:3], v135 offset:49152
	ds_read_b128 v[4:7], v135 offset:53248
	ds_read_b128 v[8:11], v135 offset:57344
	ds_read_b128 v[12:15], v135 offset:61440
	s_waitcnt lgkmcnt(4)
	v_mfma_f32_32x32x16_bf16 v[64:79], v[140:143], v[80:83], v[64:79]
	v_cvt_pk_bf16_f32 v88, v88, v89
	v_mfma_f32_32x32x16_bf16 v[48:63], v[144:147], v[80:83], v[48:63]
	v_cvt_pk_bf16_f32 v89, v90, v91
	v_mfma_f32_32x32x16_bf16 v[32:47], v[148:151], v[80:83], v[32:47]
	v_cvt_pk_bf16_f32 v90, v92, v93
	v_mfma_f32_32x32x16_bf16 v[16:31], v[152:155], v[80:83], v[16:31]
	v_cvt_pk_bf16_f32 v91, v94, v95
	s_waitcnt lgkmcnt(0)
	s_nop 0
	v_mfma_f32_32x32x16_bf16 v[64:79], v[0:3], v[88:91], v[64:79]
	v_mfma_f32_32x32x16_bf16 v[48:63], v[4:7], v[88:91], v[48:63]
	v_mfma_f32_32x32x16_bf16 v[32:47], v[8:11], v[88:91], v[32:47]
	v_mfma_f32_32x32x16_bf16 v[16:31], v[12:15], v[88:91], v[16:31]
	s_add_i32 s31, s31, 1
	s_waitcnt vmcnt(3)
	s_waitcnt lgkmcnt(0)
	s_barrier
	s_cmp_lg_u32 s31, s20
	s_cbranch_scc0 .Ldf_exit2
	s_branch .LBB0_296
.Ldf_exit0:
	v_mov_b32_e32 v0, 0x6000
	s_branch .Ldf_exitc
.Ldf_exit1:
	v_mov_b32_e32 v0, 0xc000
	s_branch .Ldf_exitc
.Ldf_exit2:
	v_mov_b32_e32 v0, 0x0
.Ldf_exitc:
	v_mov_b32_e32 v1, 0
	v_readfirstlane_b32 s101, v204
	s_nop 0
	s_lshr_b32 s101, s101, 8
	s_branch .LBB0_300
; #define MFMA(a, b, c) __builtin_amdgcn_mfma_f32_32x32x16_bf16((a), (b), (c), 0, 0, 0)
; DI float fexp2(float x) { return __builtin_amdgcn_exp2f(x); }
; template <int DV, bool NA> ...
;     ...
;       {
;         bf16x8 ka[4], kb_[4];
; #pragma unroll
;         for (int ks = 0; ks < 4; ++ks) {
;           const int co = ((2 * ks + h) ^ ksw) << 4;
;           ka[ks] = *(const bf16x8*)(st + pr * 128 + co);
;           kb_[ks] = *(const bf16x8*)(st + (32 + pr) * 128 + co);
;         }
;         asm volatile("" ::: "memory");
; #pragma unroll
;         for (int ks = 0; ks < 4; ++ks) {
;           s0 = MFMA(ka[ks], q[ks], s0);
;           s1 = MFMA(kb_[ks], q[ks], s1);
;         }
;     ...
;       float mx = t[0];
; #pragma unroll
;       for (int e = 1; e < 32; ++e) mx = fmaxf(mx, t[e]);
;       mx = fmaxf(mx, __shfl_xor(mx, 32));
;       if (__builtin_amdgcn_ballot_w64(mx > m_run + 8.f) != 0ull) {
;         const float m_new = fmaxf(m_run, mx);
;         const float alpha = fexp2(m_run - m_new);
;         l_run *= alpha;
;         m_run = m_new;
; #pragma unroll
;         for (int mv = 0; mv < DV / 32; ++mv)
; #pragma unroll
;           for (int i = 0; i < 16; ++i) o[mv][i] *= alpha;
;       }
;       float ls = 0.f;
; #pragma unroll
;       for (int e = 0; e < 32; ++e) { t[e] = fexp2(t[e] - m_run); ls += t[e]; }
;       l_run += ls;
.Ldf_fixin0:
	s_mov_b32 s22, 0x0
	s_branch .Ldf_fix
.Ldf_fixin1:
	s_mov_b32 s22, 0x6000
	s_branch .Ldf_fix
.Ldf_fixin2:
	s_mov_b32 s22, 0xc000
.Ldf_fix:
	s_waitcnt lgkmcnt(0)
	v_add_u32_e32 v158, s22, v228
	v_add_u32_e32 v159, v158, v229
	ds_read_b128 v[0:3], v159
	ds_read_b128 v[4:7], v159 offset:4096
	v_add_u32_e32 v159, v158, v202
	ds_read_b128 v[8:11], v159
	ds_read_b128 v[12:15], v159 offset:4096
	s_waitcnt lgkmcnt(2)
	v_mfma_f32_32x32x16_bf16 v[96:111], v[0:3], v[124:127], v[234:249]
	v_mfma_f32_32x32x16_bf16 v[80:95], v[4:7], v[124:127], v[234:249]
	v_add_u32_e32 v159, v158, v201
	ds_read_b128 v[0:3], v159
	ds_read_b128 v[4:7], v159 offset:4096
	s_waitcnt lgkmcnt(2)
	v_mfma_f32_32x32x16_bf16 v[96:111], v[8:11], v[120:123], v[96:111]
	v_mfma_f32_32x32x16_bf16 v[80:95], v[12:15], v[120:123], v[80:95]
	v_add_u32_e32 v159, v158, v200
	ds_read_b128 v[8:11], v159
	ds_read_b128 v[12:15], v159 offset:4096
	v_add3_u32 v230, s22, v183, v178
	s_waitcnt lgkmcnt(2)
	v_mfma_f32_32x32x16_bf16 v[96:111], v[0:3], v[116:119], v[96:111]
	v_mfma_f32_32x32x16_bf16 v[80:95], v[4:7], v[116:119], v[80:95]
	s_waitcnt lgkmcnt(0)
	v_mfma_f32_32x32x16_bf16 v[96:111], v[8:11], v[112:115], v[96:111]
	v_mfma_f32_32x32x16_bf16 v[80:95], v[12:15], v[112:115], v[80:95]
	ds_read_b128 v[0:3], v230 offset:8192
	ds_read_b128 v[4:7], v230 offset:12288
	ds_read_b128 v[8:11], v230 offset:16384
	ds_read_b128 v[12:15], v230 offset:20480
	s_nop 6
	v_max3_f32 v156, v96, v97, v98
	v_max3_f32 v157, v105, v106, v107
	v_max3_f32 v158, v80, v81, v82
	v_max3_f32 v159, v89, v90, v91
	v_max3_f32 v156, v156, v99, v100
	v_max3_f32 v157, v157, v108, v109
	v_max3_f32 v158, v158, v83, v84
	v_max3_f32 v159, v159, v92, v93
	v_max3_f32 v156, v156, v101, v102
	v_max3_f32 v157, v157, v110, v111
	v_max3_f32 v158, v158, v85, v86
	v_max3_f32 v159, v159, v94, v95
	v_max3_f32 v156, v156, v103, v104
	v_max3_f32 v158, v158, v87, v88
	v_max3_f32 v156, v156, v157, v158
	v_max_f32_e32 v156, v156, v159
	v_mov_b32_e32 v157, v156
	v_mov_b32_e32 v158, s100
	s_nop 0
	v_permlane32_swap_b32_e32 v156, v157
	v_max_f32_e32 v156, v156, v157
	v_max_f32_e32 v158, 0xff800000, v158
	v_cmp_class_f32_e64 vcc, v158, 4
	v_max_f32_e32 v157, 0, v156
	s_nop 1
	v_cndmask_b32_e32 v157, v157, v156, vcc
	s_mov_b32 s100, 0x5d800000
	v_add_f32_e32 v182, v182, v157
	v_min_f32_e64 v158, -v157, 0
	v_exp_f32_e32 v158, v158
	v_sub_f32_e32 v234, v234, v157
	v_sub_f32_e32 v235, v235, v157
	v_sub_f32_e32 v236, v236, v157
	v_sub_f32_e32 v237, v237, v157
	v_sub_f32_e32 v238, v238, v157
	v_sub_f32_e32 v239, v239, v157
	v_sub_f32_e32 v240, v240, v157
	v_sub_f32_e32 v241, v241, v157
	v_sub_f32_e32 v242, v242, v157
	v_sub_f32_e32 v243, v243, v157
	v_sub_f32_e32 v244, v244, v157
	v_sub_f32_e32 v245, v245, v157
	v_sub_f32_e32 v246, v246, v157
	v_sub_f32_e32 v247, v247, v157
	v_sub_f32_e32 v248, v248, v157
	v_sub_f32_e32 v249, v249, v157
	v_sub_f32_e32 v80, v80, v157
	v_sub_f32_e32 v81, v81, v157
	v_sub_f32_e32 v82, v82, v157
	v_sub_f32_e32 v83, v83, v157
	v_sub_f32_e32 v84, v84, v157
	v_sub_f32_e32 v85, v85, v157
	v_sub_f32_e32 v86, v86, v157
	v_sub_f32_e32 v87, v87, v157
	v_sub_f32_e32 v88, v88, v157
	v_sub_f32_e32 v89, v89, v157
	v_sub_f32_e32 v90, v90, v157
	v_sub_f32_e32 v91, v91, v157
	v_sub_f32_e32 v92, v92, v157
	v_sub_f32_e32 v93, v93, v157
	v_sub_f32_e32 v94, v94, v157
	v_sub_f32_e32 v95, v95, v157
	v_sub_f32_e32 v96, v96, v157
	v_sub_f32_e32 v97, v97, v157
	v_sub_f32_e32 v98, v98, v157
	v_sub_f32_e32 v99, v99, v157
	v_sub_f32_e32 v100, v100, v157
	v_sub_f32_e32 v101, v101, v157
	v_sub_f32_e32 v102, v102, v157
	v_sub_f32_e32 v103, v103, v157
	v_sub_f32_e32 v104, v104, v157
	v_sub_f32_e32 v105, v105, v157
	v_sub_f32_e32 v106, v106, v157
	v_sub_f32_e32 v107, v107, v157
	v_sub_f32_e32 v108, v108, v157
	v_sub_f32_e32 v109, v109, v157
	v_sub_f32_e32 v110, v110, v157
	v_sub_f32_e32 v111, v111, v157
	v_pk_mul_f32 v[16:17], v[16:17], v[158:159] op_sel_hi:[1,0]
	v_pk_mul_f32 v[18:19], v[18:19], v[158:159] op_sel_hi:[1,0]
	v_pk_mul_f32 v[20:21], v[20:21], v[158:159] op_sel_hi:[1,0]
	v_pk_mul_f32 v[22:23], v[22:23], v[158:159] op_sel_hi:[1,0]
	v_pk_mul_f32 v[24:25], v[24:25], v[158:159] op_sel_hi:[1,0]
	v_pk_mul_f32 v[26:27], v[26:27], v[158:159] op_sel_hi:[1,0]
	v_pk_mul_f32 v[28:29], v[28:29], v[158:159] op_sel_hi:[1,0]
	v_pk_mul_f32 v[30:31], v[30:31], v[158:159] op_sel_hi:[1,0]
	v_pk_mul_f32 v[32:33], v[32:33], v[158:159] op_sel_hi:[1,0]
	v_pk_mul_f32 v[34:35], v[34:35], v[158:159] op_sel_hi:[1,0]
	v_pk_mul_f32 v[36:37], v[36:37], v[158:159] op_sel_hi:[1,0]
	v_pk_mul_f32 v[38:39], v[38:39], v[158:159] op_sel_hi:[1,0]
	v_pk_mul_f32 v[40:41], v[40:41], v[158:159] op_sel_hi:[1,0]
	v_pk_mul_f32 v[42:43], v[42:43], v[158:159] op_sel_hi:[1,0]
	v_pk_mul_f32 v[44:45], v[44:45], v[158:159] op_sel_hi:[1,0]
	v_pk_mul_f32 v[46:47], v[46:47], v[158:159] op_sel_hi:[1,0]
	v_pk_mul_f32 v[48:49], v[48:49], v[158:159] op_sel_hi:[1,0]
	v_pk_mul_f32 v[50:51], v[50:51], v[158:159] op_sel_hi:[1,0]
	v_pk_mul_f32 v[52:53], v[52:53], v[158:159] op_sel_hi:[1,0]
	v_pk_mul_f32 v[54:55], v[54:55], v[158:159] op_sel_hi:[1,0]
	v_pk_mul_f32 v[56:57], v[56:57], v[158:159] op_sel_hi:[1,0]
	v_pk_mul_f32 v[58:59], v[58:59], v[158:159] op_sel_hi:[1,0]
	v_pk_mul_f32 v[60:61], v[60:61], v[158:159] op_sel_hi:[1,0]
	v_pk_mul_f32 v[62:63], v[62:63], v[158:159] op_sel_hi:[1,0]
	v_pk_mul_f32 v[64:65], v[64:65], v[158:159] op_sel_hi:[1,0]
	v_pk_mul_f32 v[66:67], v[66:67], v[158:159] op_sel_hi:[1,0]
	v_pk_mul_f32 v[68:69], v[68:69], v[158:159] op_sel_hi:[1,0]
	v_pk_mul_f32 v[70:71], v[70:71], v[158:159] op_sel_hi:[1,0]
	v_pk_mul_f32 v[72:73], v[72:73], v[158:159] op_sel_hi:[1,0]
	v_pk_mul_f32 v[74:75], v[74:75], v[158:159] op_sel_hi:[1,0]
	v_pk_mul_f32 v[76:77], v[76:77], v[158:159] op_sel_hi:[1,0]
	v_pk_mul_f32 v[78:79], v[78:79], v[158:159] op_sel_hi:[1,0]
	v_mul_f32_e32 v180, v180, v158
	s_cmp_eq_u32 s22, 0
	s_cbranch_scc1 .Ldf_exps0
	s_cmp_eq_u32 s22, 0x6000
	s_cbranch_scc1 .Ldf_exps1
	s_branch .Ldf_exps2
